# grid barrier: acquire-invalidate issued at arrival (CU quiescent while waiting) and by the XCD leader together with its release write-back, instead of after the release is observed; on top of v14
# speedup vs baseline: 1.0018x; 1.0018x over previous
.LBB0_485:
	v_readlane_b32 s2, v254, 13
	v_readlane_b32 s3, v254, 14
	v_mov_b32_e32 v1, 1
	v_sub_u32_e32 v4, 0, v2
	s_nop 2
	buffer_inv sc1
	global_atomic_add v3, v129, v1, s[2:3] sc0
	v_cvt_f32_u32_e32 v1, v2
	v_rcp_iflag_f32_e32 v1, v1
	s_nop 0
	v_mul_f32_e32 v1, 0x4f7ffffe, v1
	v_cvt_u32_f32_e32 v1, v1
	v_mul_lo_u32 v4, v4, v1
	v_mul_hi_u32 v4, v1, v4
	v_add_u32_e32 v1, v1, v4
	s_waitcnt vmcnt(0)
	v_mul_hi_u32 v1, v3, v1
	v_mul_lo_u32 v4, v1, v2
	v_sub_u32_e32 v4, v3, v4
	v_add_u32_e32 v5, 1, v1
	v_cmp_ge_u32_e32 vcc, v4, v2
	v_add_u32_e32 v3, 1, v3
	s_nop 0
	v_cndmask_b32_e32 v1, v1, v5, vcc
	v_sub_u32_e32 v5, v4, v2
	v_cndmask_b32_e32 v4, v4, v5, vcc
	v_add_u32_e32 v5, 1, v1
	v_cmp_ge_u32_e32 vcc, v4, v2
	s_nop 1
	v_cndmask_b32_e32 v1, v1, v5, vcc
	v_mul_lo_u32 v4, v2, v1
	v_add_u32_e32 v2, v4, v2
	v_cmp_ne_u32_e32 vcc, v3, v2
	s_and_saveexec_b64 s[2:3], vcc
	s_xor_b64 s[2:3], exec, s[2:3]
	s_cbranch_execz .LBB0_499
	v_readlane_b32 s4, v254, 15
	v_readlane_b32 s5, v254, 16
	s_waitcnt lgkmcnt(0)
	s_nop 3
	global_load_dword v0, v129, s[4:5] sc1
	s_waitcnt vmcnt(0)
	v_cmp_eq_u32_e32 vcc, v0, v1
	s_and_saveexec_b64 s[10:11], vcc
	s_cbranch_execz .LBB0_498
	s_mov_b32 s4, 1
	s_mov_b64 s[12:13], 0
	s_branch .LBB0_489

.LBB0_499:
	s_andn2_saveexec_b64 s[2:3], s[2:3]
	s_cbranch_execz .LBB0_517
	s_mov_b64 s[2:3], exec
	buffer_wbl2 sc1
	buffer_inv sc1
	s_waitcnt lgkmcnt(0)
	s_waitcnt vmcnt(0)
	v_mbcnt_lo_u32_b32 v1, s2, 0
	v_mbcnt_hi_u32_b32 v1, s3, v1
	v_cmp_eq_u32_e32 vcc, 0, v1
	s_and_saveexec_b64 s[10:11], vcc
	s_cbranch_execz .LBB0_502
	s_bcnt1_i32_b64 s2, s[2:3]
	v_mov_b32_e32 v2, s2
	v_readlane_b32 s2, v254, 17
	v_readlane_b32 s3, v254, 18
	s_nop 4
	global_atomic_add v2, v129, v2, s[2:3] sc0

.LBB0_516:
	s_or_b64 exec, exec, s[2:3]
	v_readlane_b32 s2, v254, 15
	v_readlane_b32 s3, v254, 16
	v_mov_b32_e32 v0, 1
	s_waitcnt vmcnt(0)
	s_nop 1
	global_atomic_add v129, v0, s[2:3]
	s_waitcnt vmcnt(0)

.LBB0_810:
	v_readlane_b32 s4, v254, 13
	v_readlane_b32 s5, v254, 14
	v_mov_b32_e32 v1, 1
	v_sub_u32_e32 v4, 0, v2
	s_nop 2
	buffer_inv sc1
	global_atomic_add v3, v129, v1, s[4:5] sc0
	v_cvt_f32_u32_e32 v1, v2
	v_rcp_iflag_f32_e32 v1, v1
	s_nop 0
	v_mul_f32_e32 v1, 0x4f7ffffe, v1
	v_cvt_u32_f32_e32 v1, v1
	v_mul_lo_u32 v4, v4, v1
	v_mul_hi_u32 v4, v1, v4
	v_add_u32_e32 v1, v1, v4
	s_waitcnt vmcnt(0)
	v_mul_hi_u32 v1, v3, v1
	v_mul_lo_u32 v4, v1, v2
	v_sub_u32_e32 v4, v3, v4
	v_add_u32_e32 v5, 1, v1
	v_cmp_ge_u32_e32 vcc, v4, v2
	v_add_u32_e32 v3, 1, v3
	s_nop 0
	v_cndmask_b32_e32 v1, v1, v5, vcc
	v_sub_u32_e32 v5, v4, v2
	v_cndmask_b32_e32 v4, v4, v5, vcc
	v_add_u32_e32 v5, 1, v1
	v_cmp_ge_u32_e32 vcc, v4, v2
	s_nop 1
	v_cndmask_b32_e32 v1, v1, v5, vcc
	v_mul_lo_u32 v4, v2, v1
	v_add_u32_e32 v2, v4, v2
	v_cmp_ne_u32_e32 vcc, v3, v2
	s_and_saveexec_b64 s[4:5], vcc
	s_xor_b64 s[10:11], exec, s[4:5]
	s_cbranch_execz .LBB0_824
	v_readlane_b32 s4, v254, 15
	v_readlane_b32 s5, v254, 16
	s_waitcnt lgkmcnt(0)
	s_nop 3
	global_load_dword v0, v129, s[4:5] sc1
	s_waitcnt vmcnt(0)
	v_cmp_eq_u32_e32 vcc, v0, v1
	s_and_saveexec_b64 s[12:13], vcc
	s_cbranch_execz .LBB0_823
	s_mov_b32 s4, 1
	s_mov_b64 s[14:15], 0
	s_branch .LBB0_814

.LBB0_824:
	s_andn2_saveexec_b64 s[4:5], s[10:11]
	s_cbranch_execz .LBB0_842
	s_mov_b64 s[10:11], exec
	buffer_wbl2 sc1
	buffer_inv sc1
	s_waitcnt lgkmcnt(0)
	s_waitcnt vmcnt(0)
	v_mbcnt_lo_u32_b32 v1, s10, 0
	v_mbcnt_hi_u32_b32 v1, s11, v1
	v_cmp_eq_u32_e32 vcc, 0, v1
	s_and_saveexec_b64 s[12:13], vcc
	s_cbranch_execz .LBB0_827
	s_bcnt1_i32_b64 s4, s[10:11]
	v_mov_b32_e32 v2, s4
	v_readlane_b32 s4, v254, 17
	v_readlane_b32 s5, v254, 18
	s_nop 4
	global_atomic_add v2, v129, v2, s[4:5] sc0

.LBB0_841:
	s_or_b64 exec, exec, s[10:11]
	v_readlane_b32 s4, v254, 15
	v_readlane_b32 s5, v254, 16
	v_mov_b32_e32 v0, 1
	s_waitcnt vmcnt(0)
	s_nop 1
	global_atomic_add v129, v0, s[4:5]
	s_waitcnt vmcnt(0)
